# half of the second row-sum chain also moved into the MFMA shadow; chains joined at the end
# baseline (speedup 1.0000x reference)
.Lcj_cx_0:
	v_add_f32_e32 v80, v89, v80
	v_add_f32_e32 v80, v90, v80
	v_add_f32_e32 v80, v91, v80
	v_add_f32_e32 v80, v92, v80
	v_add_f32_e32 v80, v93, v80
	v_add_f32_e32 v80, v94, v80
	v_add_f32_e32 v80, v95, v80
	v_add_f32_e32 v135, v80, v96
	s_branch .Lcj_common_0
.Lcj_c5_0:
	v_add_f32_e32 v80, v89, v80
	s_waitcnt vmcnt(6)
	v_cvt_pk_bf16_f32 v224, v224, v228
	v_cvt_pk_bf16_f32 v228, v225, v229
	v_cvt_pk_bf16_f32 v225, v232, v236
	v_cvt_pk_bf16_f32 v232, v226, v230
	v_cvt_pk_bf16_f32 v226, v240, v244
	v_cvt_pk_bf16_f32 v236, v227, v231
	v_cvt_pk_bf16_f32 v227, v248, v252
	v_add_f32_e32 v80, v90, v80
	v_cvt_pk_bf16_f32 v229, v233, v237
	v_cvt_pk_bf16_f32 v230, v241, v245
	v_cvt_pk_bf16_f32 v231, v249, v253
	v_cvt_pk_bf16_f32 v233, v234, v238
	v_cvt_pk_bf16_f32 v234, v242, v246
	v_cvt_pk_bf16_f32 v237, v235, v239
	v_cvt_pk_bf16_f32 v235, v250, v254
	v_cvt_pk_bf16_f32 v238, v243, v247
	v_add_f32_e32 v80, v91, v80
	v_cvt_pk_bf16_f32 v239, v251, v255
	s_lshr_b32 s91, s2, 7
	s_lshl_b32 s92, s98, 1
	s_add_i32 s91, s91, s92
	s_mul_i32 s92, s91, 0xab
	s_lshr_b32 s92, s92, 9
	s_mul_i32 s93, s92, 3
	s_sub_i32 s91, s91, s93
	v_add_f32_e32 v80, v92, v80
	v_mbcnt_lo_u32_b32 v222, -1, 0
	v_mbcnt_hi_u32_b32 v222, -1, v222
	s_and_b32 s93, s2, 0x7f
	s_lshl_b32 s93, s93, 9
	s_or_b32 s93, s93, s63
	v_or_b32_e32 v222, s93, v222
	s_cmp_eq_u32 s91, 2
	s_cselect_b32 s93, 12, 11
	v_add_f32_e32 v80, v93, v80
	v_lshrrev_b32_e32 v223, s93, v222
	v_and_b32_e32 v208, 7, v222
	v_lshl_or_b32 v223, v223, 3, v208
	s_cselect_b32 s93, 6, 5
	v_bfe_u32 v208, v222, 6, s93
	v_lshrrev_b32_e32 v222, 1, v222
	v_and_b32_e32 v222, 28, v222
	v_lshl_or_b32 v222, v208, 5, v222
	v_add_f32_e32 v80, v94, v80
	s_cselect_b64 vcc, exec, 0
	s_cselect_b32 s94, 11, 12
	s_cselect_b64 s[100:101], s[86:87], s[84:85]
	s_cselect_b32 s93, 22, 23
	v_lshrrev_b32_e32 v208, 7, v222
	v_and_b32_e32 v240, 0x7f, v222
	s_lshl_b32 s92, s92, s93
	v_lshl_or_b32 v208, v208, 8, v240
	v_add_f32_e32 v80, v95, v80
	s_lshl_b32 s93, s91, 7
	v_or_b32_e32 v208, s93, v208
	v_cndmask_b32_e32 v222, v208, v222, vcc
	v_lshlrev_b32_e32 v222, s94, v222
	s_lshl_b32 s94, 1, s94
	v_lshl_or_b32 v222, v223, 4, v222
	s_add_u32 s100, s100, s92
	s_addc_u32 s101, s101, 0
	v_add_f32_e32 v135, v80, v96
	s_mov_b32 s95, 5
	s_branch .Lcj_common_0
.Lcj_c7_0:
	v_add_f32_e32 v80, v89, v80
	s_add_i32 s98, s98, 1
	s_min_u32 s98, s98, 47
	s_lshr_b32 s91, s2, 7
	s_lshl_b32 s92, s98, 1
	s_add_i32 s91, s91, s92
	s_mul_i32 s92, s91, 0xab
	v_add_f32_e32 v80, v90, v80
	s_lshr_b32 s92, s92, 9
	s_mul_i32 s93, s92, 3
	s_sub_i32 s91, s91, s93
	v_mbcnt_lo_u32_b32 v222, -1, 0
	v_mbcnt_hi_u32_b32 v222, -1, v222
	s_and_b32 s93, s2, 0x7f
	v_add_f32_e32 v80, v91, v80
	s_lshl_b32 s93, s93, 9
	s_or_b32 s93, s93, s63
	v_or_b32_e32 v222, s93, v222
	s_cmp_eq_u32 s91, 2
	s_cselect_b32 s93, 12, 11
	v_lshrrev_b32_e32 v223, s93, v222
	v_add_f32_e32 v80, v92, v80
	v_and_b32_e32 v208, 7, v222
	v_lshl_or_b32 v223, v223, 3, v208
	s_cselect_b32 s93, 6, 5
	v_bfe_u32 v208, v222, 6, s93
	v_lshrrev_b32_e32 v222, 1, v222
	v_and_b32_e32 v222, 28, v222
	v_add_f32_e32 v80, v93, v80
	v_lshl_or_b32 v222, v208, 5, v222
	v_lshlrev_b32_e32 v222, 2, v222
	s_cselect_b32 s93, 16, 15
	v_lshlrev_b32_e32 v223, s93, v223
	v_add_u32_e32 v222, v223, v222
	s_cselect_b32 s94, 1, 0
	v_add_f32_e32 v80, v94, v80
	s_lshl_b32 s94, 0x1000, s94
	s_lshl_b32 s92, s92, 23
	s_cmp_eq_u32 s91, 0
	s_cselect_b64 s[100:101], s[76:77], s[78:79]
	s_cmp_eq_u32 s91, 2
	s_cselect_b64 s[100:101], s[80:81], s[100:101]
	v_add_f32_e32 v80, v95, v80
	s_add_u32 s100, s100, s92
	s_addc_u32 s101, s101, 0
	s_mov_b32 s95, 1
	s_cmp_lt_u32 s4, 56
	s_cselect_b32 s95, 1, 0
	v_add_f32_e32 v135, v80, v96

.Lcjh_done_0:
	ds_read_b128 v[80:83], v85 offset:2048
	ds_read_b128 v[188:191], v85 offset:2560
	v_add3_u32 v85, s34, v180, v176
	s_mov_b64 s[34:35], -1
	ds_read_b128 v[192:195], v84 offset:4608
	s_waitcnt lgkmcnt(0)
	v_mfma_f32_32x32x16_bf16 v[96:111], v[80:83], v[116:119], v[96:111]
	ds_read_b128 v[80:83], v84 offset:4096
	s_waitcnt lgkmcnt(0)
	v_mfma_f32_32x32x16_bf16 v[96:111], v[80:83], v[120:123], v[96:111]
	ds_read_b128 v[80:83], v85 offset:6144
	ds_read_b128 v[196:199], v85 offset:6656
	s_waitcnt lgkmcnt(0)
	v_mfma_f32_32x32x16_bf16 v[96:111], v[80:83], v[124:127], v[96:111]
	v_mfma_f32_32x32x16_bf16 v[80:95], v[184:187], v[112:115], v[0:15]
	ds_read_b128 v[184:187], v200 offset:16384
	s_nop 9
	v_exp_f32_e32 v96, v96
	v_exp_f32_e32 v97, v97
	v_exp_f32_e32 v98, v98
	v_exp_f32_e32 v99, v99
	v_exp_f32_e32 v100, v100
	v_exp_f32_e32 v101, v101
	v_mfma_f32_32x32x16_bf16 v[80:95], v[188:191], v[116:119], v[80:95]
	v_exp_f32_e32 v102, v102
	v_exp_f32_e32 v103, v103
	v_cvt_pk_bf16_f32 v188, v96, v97
	v_cvt_pk_bf16_f32 v189, v98, v99
	v_cvt_pk_bf16_f32 v190, v100, v101
	v_cvt_pk_bf16_f32 v191, v102, v103
	v_exp_f32_e32 v104, v104
	v_mfma_f32_32x32x16_bf16 v[80:95], v[192:195], v[120:123], v[80:95]
	ds_read_b128 v[192:195], v200 offset:17408
	v_exp_f32_e32 v105, v105
	v_exp_f32_e32 v106, v106
	v_exp_f32_e32 v107, v107
	v_exp_f32_e32 v108, v108
	v_exp_f32_e32 v109, v109
	v_exp_f32_e32 v110, v110
	v_mfma_f32_32x32x16_bf16 v[80:95], v[196:199], v[124:127], v[80:95]
	v_exp_f32_e32 v111, v111
	s_waitcnt lgkmcnt(0)
	v_mfma_f32_32x32x16_bf16 v[64:79], v[184:187], v[188:191], v[64:79]
	ds_read_b128 v[184:187], v201 offset:16896
	ds_read_b128 v[196:199], v201 offset:17920
	s_nop 6
	v_exp_f32_e32 v80, v80
	v_exp_f32_e32 v81, v81
	v_exp_f32_e32 v82, v82
	v_exp_f32_e32 v83, v83
	v_exp_f32_e32 v84, v84
	v_exp_f32_e32 v85, v85
	s_waitcnt lgkmcnt(0)
	v_mfma_f32_32x32x16_bf16 v[48:63], v[184:187], v[188:191], v[48:63]
	ds_read_b128 v[184:187], v200 offset:20480
	v_exp_f32_e32 v86, v86
	v_exp_f32_e32 v87, v87
	v_exp_f32_e32 v88, v88
	v_exp_f32_e32 v89, v89
	v_exp_f32_e32 v90, v90
	v_exp_f32_e32 v91, v91
	v_mfma_f32_32x32x16_bf16 v[32:47], v[192:195], v[188:191], v[32:47]
	ds_read_b128 v[192:195], v200 offset:21504
	v_exp_f32_e32 v92, v92
	v_exp_f32_e32 v93, v93
	v_exp_f32_e32 v94, v94
	v_exp_f32_e32 v95, v95
	v_mfma_f32_32x32x16_bf16 v[16:31], v[196:199], v[188:191], v[16:31]
	v_cvt_pk_bf16_f32 v188, v104, v105
	v_cvt_pk_bf16_f32 v189, v106, v107
	v_cvt_pk_bf16_f32 v190, v108, v109
	v_cvt_pk_bf16_f32 v191, v110, v111
	s_waitcnt lgkmcnt(0)
	s_nop 0
	v_mfma_f32_32x32x16_bf16 v[64:79], v[184:187], v[188:191], v[64:79]
	ds_read_b128 v[184:187], v201 offset:20992
	ds_read_b128 v[196:199], v201 offset:22016
	s_waitcnt lgkmcnt(0)
	v_mfma_f32_32x32x16_bf16 v[48:63], v[184:187], v[188:191], v[48:63]
	ds_read_b128 v[184:187], v200 offset:24576
	v_mfma_f32_32x32x16_bf16 v[32:47], v[192:195], v[188:191], v[32:47]
	ds_read_b128 v[192:195], v200 offset:25600
	v_mfma_f32_32x32x16_bf16 v[16:31], v[196:199], v[188:191], v[16:31]
	v_cvt_pk_bf16_f32 v188, v80, v81
	v_cvt_pk_bf16_f32 v189, v82, v83
	v_cvt_pk_bf16_f32 v190, v84, v85
	v_cvt_pk_bf16_f32 v191, v86, v87
	s_waitcnt lgkmcnt(0)
	s_nop 0
	v_mfma_f32_32x32x16_bf16 v[64:79], v[184:187], v[188:191], v[64:79]
	ds_read_b128 v[184:187], v201 offset:25088
	ds_read_b128 v[196:199], v201 offset:26112
	s_waitcnt lgkmcnt(0)
	v_mfma_f32_32x32x16_bf16 v[48:63], v[184:187], v[188:191], v[48:63]
	ds_read_b128 v[184:187], v200 offset:28672
	v_mfma_f32_32x32x16_bf16 v[32:47], v[192:195], v[188:191], v[32:47]
	ds_read_b128 v[192:195], v200 offset:29696
	v_mfma_f32_32x32x16_bf16 v[16:31], v[196:199], v[188:191], v[16:31]
	v_cvt_pk_bf16_f32 v188, v88, v89
	v_cvt_pk_bf16_f32 v189, v90, v91
	v_cvt_pk_bf16_f32 v190, v92, v93
	v_cvt_pk_bf16_f32 v191, v94, v95
	s_waitcnt lgkmcnt(0)
	s_nop 0
	v_mfma_f32_32x32x16_bf16 v[64:79], v[184:187], v[188:191], v[64:79]
	ds_read_b128 v[184:187], v201 offset:29184
	ds_read_b128 v[196:199], v201 offset:30208
	v_add_f32_e32 v80, v81, v80
	v_add_f32_e32 v80, v82, v80
	v_add_f32_e32 v80, v83, v80
	v_add_f32_e32 v80, v84, v80
	v_add_f32_e32 v80, v85, v80
	v_add_f32_e32 v80, v86, v80
	v_add_f32_e32 v80, v87, v80
	v_add_f32_e32 v80, v88, v80
	s_waitcnt lgkmcnt(0)
	v_mfma_f32_32x32x16_bf16 v[48:63], v[184:187], v[188:191], v[48:63]
	v_add_f32_e32 v96, v135, v96
	v_add_f32_e32 v96, v97, v96
	v_add_f32_e32 v96, v98, v96
	v_add_f32_e32 v96, v99, v96
	v_add_f32_e32 v96, v100, v96
	v_add_f32_e32 v96, v101, v96
	v_add_f32_e32 v96, v102, v96
	v_add_f32_e32 v96, v103, v96
	v_mfma_f32_32x32x16_bf16 v[32:47], v[192:195], v[188:191], v[32:47]
	v_add_f32_e32 v96, v104, v96
	v_add_f32_e32 v96, v105, v96
	v_add_f32_e32 v96, v106, v96
	v_add_f32_e32 v96, v107, v96
	v_add_f32_e32 v96, v108, v96
	v_add_f32_e32 v96, v109, v96
	v_add_f32_e32 v96, v110, v96
	v_add_f32_e32 v96, v111, v96
	v_mfma_f32_32x32x16_bf16 v[16:31], v[196:199], v[188:191], v[16:31]
	s_cbranch_vccz .Lcj_cnt_0
	s_waitcnt vmcnt(0)
	s_branch .LBB0_1448

.Lcjh_done_1:
	ds_read_b128 v[80:83], v85 offset:2048
	ds_read_b128 v[156:159], v85 offset:2560
	v_add3_u32 v85, s18, v180, v176
	s_mov_b64 s[18:19], -1
	ds_read_b128 v[160:163], v84 offset:4608
	s_waitcnt lgkmcnt(0)
	v_mfma_f32_32x32x16_bf16 v[96:111], v[80:83], v[116:119], v[96:111]
	ds_read_b128 v[80:83], v84 offset:4096
	s_waitcnt lgkmcnt(0)
	v_mfma_f32_32x32x16_bf16 v[96:111], v[80:83], v[120:123], v[96:111]
	ds_read_b128 v[80:83], v85 offset:6144
	ds_read_b128 v[218:221], v85 offset:6656
	s_waitcnt lgkmcnt(0)
	v_mfma_f32_32x32x16_bf16 v[96:111], v[80:83], v[124:127], v[96:111]
	v_mfma_f32_32x32x16_bf16 v[80:95], v[152:155], v[112:115], v[0:15]
	ds_read_b128 v[152:155], v209 offset:16384
	s_nop 9
	v_exp_f32_e32 v96, v96
	v_exp_f32_e32 v97, v97
	v_exp_f32_e32 v98, v98
	v_exp_f32_e32 v99, v99
	v_exp_f32_e32 v100, v100
	v_exp_f32_e32 v101, v101
	v_mfma_f32_32x32x16_bf16 v[80:95], v[156:159], v[116:119], v[80:95]
	v_exp_f32_e32 v102, v102
	v_exp_f32_e32 v103, v103
	v_cvt_pk_bf16_f32 v156, v96, v97
	v_cvt_pk_bf16_f32 v157, v98, v99
	v_cvt_pk_bf16_f32 v158, v100, v101
	v_cvt_pk_bf16_f32 v159, v102, v103
	v_exp_f32_e32 v104, v104
	v_mfma_f32_32x32x16_bf16 v[80:95], v[160:163], v[120:123], v[80:95]
	ds_read_b128 v[160:163], v209 offset:17408
	v_exp_f32_e32 v105, v105
	v_exp_f32_e32 v106, v106
	v_exp_f32_e32 v107, v107
	v_exp_f32_e32 v108, v108
	v_exp_f32_e32 v109, v109
	v_exp_f32_e32 v110, v110
	v_mfma_f32_32x32x16_bf16 v[80:95], v[218:221], v[124:127], v[80:95]
	v_exp_f32_e32 v111, v111
	s_waitcnt lgkmcnt(0)
	v_mfma_f32_32x32x16_bf16 v[64:79], v[152:155], v[156:159], v[64:79]
	ds_read_b128 v[152:155], v211 offset:16896
	ds_read_b128 v[218:221], v211 offset:17920
	s_nop 6
	v_exp_f32_e32 v80, v80
	v_exp_f32_e32 v81, v81
	v_exp_f32_e32 v82, v82
	v_exp_f32_e32 v83, v83
	v_exp_f32_e32 v84, v84
	v_exp_f32_e32 v85, v85
	s_waitcnt lgkmcnt(0)
	v_mfma_f32_32x32x16_bf16 v[48:63], v[152:155], v[156:159], v[48:63]
	ds_read_b128 v[152:155], v209 offset:20480
	v_exp_f32_e32 v86, v86
	v_exp_f32_e32 v87, v87
	v_exp_f32_e32 v88, v88
	v_exp_f32_e32 v89, v89
	v_exp_f32_e32 v90, v90
	v_exp_f32_e32 v91, v91
	v_mfma_f32_32x32x16_bf16 v[32:47], v[160:163], v[156:159], v[32:47]
	ds_read_b128 v[160:163], v209 offset:21504
	v_exp_f32_e32 v92, v92
	v_exp_f32_e32 v93, v93
	v_exp_f32_e32 v94, v94
	v_exp_f32_e32 v95, v95
	v_mfma_f32_32x32x16_bf16 v[16:31], v[218:221], v[156:159], v[16:31]
	v_cvt_pk_bf16_f32 v156, v104, v105
	v_cvt_pk_bf16_f32 v157, v106, v107
	v_cvt_pk_bf16_f32 v158, v108, v109
	v_cvt_pk_bf16_f32 v159, v110, v111
	s_waitcnt lgkmcnt(0)
	s_nop 0
	v_mfma_f32_32x32x16_bf16 v[64:79], v[152:155], v[156:159], v[64:79]
	ds_read_b128 v[152:155], v211 offset:20992
	ds_read_b128 v[218:221], v211 offset:22016
	s_waitcnt lgkmcnt(0)
	v_mfma_f32_32x32x16_bf16 v[48:63], v[152:155], v[156:159], v[48:63]
	ds_read_b128 v[152:155], v209 offset:24576
	v_mfma_f32_32x32x16_bf16 v[32:47], v[160:163], v[156:159], v[32:47]
	ds_read_b128 v[160:163], v209 offset:25600
	v_mfma_f32_32x32x16_bf16 v[16:31], v[218:221], v[156:159], v[16:31]
	v_cvt_pk_bf16_f32 v156, v80, v81
	v_cvt_pk_bf16_f32 v157, v82, v83
	v_cvt_pk_bf16_f32 v158, v84, v85
	v_cvt_pk_bf16_f32 v159, v86, v87
	s_waitcnt lgkmcnt(0)
	s_nop 0
	v_mfma_f32_32x32x16_bf16 v[64:79], v[152:155], v[156:159], v[64:79]
	ds_read_b128 v[152:155], v211 offset:25088
	ds_read_b128 v[218:221], v211 offset:26112
	s_waitcnt lgkmcnt(0)
	v_mfma_f32_32x32x16_bf16 v[48:63], v[152:155], v[156:159], v[48:63]
	ds_read_b128 v[152:155], v209 offset:28672
	v_mfma_f32_32x32x16_bf16 v[32:47], v[160:163], v[156:159], v[32:47]
	ds_read_b128 v[160:163], v209 offset:29696
	v_mfma_f32_32x32x16_bf16 v[16:31], v[218:221], v[156:159], v[16:31]
	v_cvt_pk_bf16_f32 v156, v88, v89
	v_cvt_pk_bf16_f32 v157, v90, v91
	v_cvt_pk_bf16_f32 v158, v92, v93
	v_cvt_pk_bf16_f32 v159, v94, v95
	s_waitcnt lgkmcnt(0)
	s_nop 0
	v_mfma_f32_32x32x16_bf16 v[64:79], v[152:155], v[156:159], v[64:79]
	ds_read_b128 v[152:155], v211 offset:29184
	ds_read_b128 v[218:221], v211 offset:30208
	v_add_f32_e32 v80, v81, v80
	v_add_f32_e32 v80, v82, v80
	v_add_f32_e32 v80, v83, v80
	v_add_f32_e32 v80, v84, v80
	v_add_f32_e32 v80, v85, v80
	v_add_f32_e32 v80, v86, v80
	v_add_f32_e32 v80, v87, v80
	v_add_f32_e32 v80, v88, v80
	s_waitcnt lgkmcnt(0)
	v_mfma_f32_32x32x16_bf16 v[48:63], v[152:155], v[156:159], v[48:63]
	v_add_f32_e32 v96, v135, v96
	v_add_f32_e32 v96, v97, v96
	v_add_f32_e32 v96, v98, v96
	v_add_f32_e32 v96, v99, v96
	v_add_f32_e32 v96, v100, v96
	v_add_f32_e32 v96, v101, v96
	v_add_f32_e32 v96, v102, v96
	v_add_f32_e32 v96, v103, v96
	v_mfma_f32_32x32x16_bf16 v[32:47], v[160:163], v[156:159], v[32:47]
	v_add_f32_e32 v96, v104, v96
	v_add_f32_e32 v96, v105, v96
	v_add_f32_e32 v96, v106, v96
	v_add_f32_e32 v96, v107, v96
	v_add_f32_e32 v96, v108, v96
	v_add_f32_e32 v96, v109, v96
	v_add_f32_e32 v96, v110, v96
	v_add_f32_e32 v96, v111, v96
	v_mfma_f32_32x32x16_bf16 v[16:31], v[218:221], v[156:159], v[16:31]
	s_cbranch_vccz .Lcj_cnt_1
	s_waitcnt vmcnt(0)
	s_branch .LBB0_1456
